# GEMM phase prologue de-serialisation: all 14 first-tile LDS-DMA loads issued before the first wait (vmcnt(2)->vmcnt(8), barrier moved after the second load group) in all 12 GEMM instances; on top of v
# speedup vs baseline: 1.0009x; 1.0009x over previous
.LBB0_457:
	s_add_i32 s47, s78, 0x7300
	s_add_u32 s28, s4, 0x8ac0000
	s_addc_u32 s18, s5, 0
	v_readlane_b32 s88, v254, 59
	s_add_u32 s88, s4, 0x46c0000
	s_addc_u32 s19, s5, 0
	s_add_u32 s8, s4, 0x4280000
	s_addc_u32 s9, s5, 0
	s_lshl_b64 s[16:17], s[48:49], 2
	s_waitcnt lgkmcnt(0)
	s_add_u32 s10, s10, s16
	s_addc_u32 s11, s11, s17
	s_and_b32 s16, s14, 3
	s_add_i32 m0, s37, 0x18000
	v_lshl_add_u64 v[6:7], v[6:7], 0, s[96:97]
	s_mov_b64 s[86:87], s[48:49]
	s_lshl_b32 s48, s13, 6
	s_lshl_b32 s13, s13, 13
	s_lshl_b32 s49, s16, 5
	s_lshl_b32 s17, s16, 12
	global_load_lds_dwordx4 v[6:7], off
	v_lshl_add_u64 v[4:5], v[4:5], 0, s[96:97]
	s_add_i32 m0, s37, 0x1a000
	s_add_i32 s51, s37, 0x8000
	s_add_i32 s52, s37, 0xa000
	global_load_lds_dwordx4 v[4:5], off
	v_lshl_add_u64 v[0:1], v[0:1], 0, s[96:97]
	s_mov_b32 m0, s51
	s_add_u32 s14, s2, 0x40080
	global_load_lds_dwordx4 v[0:1], off
	v_lshl_add_u64 v[0:1], v[2:3], 0, s[96:97]
	s_mov_b32 m0, s52
	s_addc_u32 s15, s3, 0
	global_load_lds_dwordx4 v[0:1], off
	s_add_i32 m0, s37, 0x1c000
	v_lshl_add_u64 v[0:1], s[14:15], 0, v[64:65]
	global_load_lds_dwordx4 v[0:1], off
	v_lshl_add_u64 v[0:1], s[14:15], 0, v[138:139]
	s_add_i32 m0, s37, 0x1e000
	s_movk_i32 s14, 0x3c0
	global_load_lds_dwordx4 v[0:1], off
	s_waitcnt vmcnt(8)
	s_barrier
	v_and_b32_e32 v0, 48, v10
	v_lshlrev_b32_e32 v1, 6, v10
	v_and_or_b32 v0, v1, s14, v0
	v_lshlrev_b32_e32 v1, 2, v10
	v_and_b32_e32 v1, 32, v1
	v_bitop3_b32 v2, v0, s13, v1 bitop3:0xde
	v_bitop3_b32 v152, v0, s17, v1 bitop3:0xde
	v_lshlrev_b32_e32 v0, 14, v13
	v_and_b32_e32 v0, 0xffff8000, v0
	s_cmpk_lt_u32 s12, 0x100
	v_readlane_b32 s56, v254, 43
	v_lshl_add_u32 v0, v12, 11, v0
	v_and_b32_e32 v1, 1, v13
	v_readlane_b32 s89, v254, 60
	v_readlane_b32 s91, v254, 62
	s_cselect_b64 s[12:13], -1, 0
	s_cmp_lt_u32 s16, 2
	v_readlane_b32 s59, v254, 46
	v_lshl_or_b32 v0, v1, 6, v0
	v_readlane_b32 s90, v254, 61
	s_cselect_b64 s[14:15], -1, 0
	s_and_b32 s89, s19, 0xffff
	s_mov_b32 s91, s59
	v_lshl_add_u32 v144, v14, 1, v0
	v_lshlrev_b32_e32 v0, 14, v8
	s_lshl_b32 s53, s16, 6
	v_readlane_b32 s57, v254, 44
	v_readlane_b32 s58, v254, 45
	v_writelane_b32 v254, s88, 59
	v_and_b32_e32 v0, 0xffff8000, v0
	v_readlane_b32 s16, v253, 59
	s_waitcnt vmcnt(6)
	v_writelane_b32 v254, s89, 60
	v_lshl_add_u32 v0, v9, 11, v0
	v_and_b32_e32 v1, 1, v8
	v_readlane_b32 s17, v253, 60
	v_writelane_b32 v254, s90, 61
	v_lshl_or_b32 v0, v1, 6, v0
	s_mov_b32 s56, s16
	v_readlane_b32 s16, v253, 55
	s_and_b32 s29, s18, 0xffff
	s_mov_b32 s31, s59
	v_writelane_b32 v254, s91, 62
	v_mov_b32_e32 v145, v65
	v_lshl_add_u32 v146, v11, 1, v0
	v_mov_b32_e32 v147, v65
	s_mov_b32 s54, 0
	v_add_u32_e32 v153, 0, v2
	s_mov_b32 s55, s16
	s_barrier
	v_readlane_b32 s17, v253, 56
	s_branch .LBB0_460

.LBB0_1300:
	v_readlane_b32 s12, v255, 8
	s_add_i32 s48, s12, 0x4000
	v_readlane_b32 s13, v255, 9
	s_add_u32 s12, s4, 0x46c0000
	s_addc_u32 s13, s5, 0
	s_add_u32 s14, s4, 0x8ac0000
	s_addc_u32 s15, s5, 0
	s_add_u32 s40, s4, 0xcec0000
	s_addc_u32 s20, s5, 0
	s_and_b32 s21, s17, 3
	s_lshl_b32 s49, s18, 6
	v_and_b32_e32 v15, 48, v14
	s_lshl_b32 s17, s18, 13
	v_lshlrev_b32_e32 v16, 6, v14
	s_movk_i32 s18, 0x3c0
	v_lshlrev_b32_e32 v14, 2, v14
	v_and_or_b32 v15, v16, s18, v15
	v_and_b32_e32 v14, 32, v14
	s_add_i32 m0, s7, 0x18000
	v_lshl_add_u64 v[6:7], v[6:7], 0, s[96:97]
	v_bitop3_b32 v16, v15, s17, v14 bitop3:0xde
	s_lshl_b32 s51, s21, 5
	s_lshl_b32 s17, s21, 12
	global_load_lds_dwordx4 v[6:7], off
	v_lshl_add_u64 v[4:5], v[4:5], 0, s[96:97]
	s_add_i32 m0, s7, 0x1a000
	s_add_i32 s52, s7, 0x8000
	s_add_i32 s53, s7, 0xa000
	global_load_lds_dwordx4 v[4:5], off
	v_lshl_add_u64 v[0:1], v[0:1], 0, s[96:97]
	s_mov_b32 m0, s52
	s_add_u32 s18, s2, 0x40080
	global_load_lds_dwordx4 v[0:1], off
	v_lshl_add_u64 v[0:1], v[2:3], 0, s[96:97]
	s_mov_b32 m0, s53
	s_addc_u32 s19, s3, 0
	global_load_lds_dwordx4 v[0:1], off
	s_add_i32 m0, s7, 0x1c000
	v_lshl_add_u64 v[0:1], s[18:19], 0, v[64:65]
	global_load_lds_dwordx4 v[0:1], off
	v_lshl_add_u64 v[0:1], s[18:19], 0, v[202:203]
	s_add_i32 m0, s7, 0x1e000
	s_cmpk_lt_u32 s16, 0x100
	global_load_lds_dwordx4 v[0:1], off
	s_waitcnt vmcnt(8)
	s_barrier
	v_lshlrev_b32_e32 v0, 14, v8
	v_and_b32_e32 v0, 0xffff8000, v0
	v_lshl_add_u32 v0, v9, 11, v0
	v_and_b32_e32 v1, 1, v8
	v_lshl_or_b32 v0, v1, 6, v0
	v_lshl_add_u32 v204, v10, 1, v0
	v_lshlrev_b32_e32 v0, 14, v11
	v_bitop3_b32 v242, v15, s17, v14 bitop3:0xde
	s_cselect_b64 s[16:17], -1, 0
	s_lshl_b32 s18, s21, 6
	v_and_b32_e32 v0, 0xffff8000, v0
	s_waitcnt vmcnt(6)
	s_or_b32 s55, s18, 0xfffff000
	s_lshl_b32 s18, s21, 2
	s_and_b32 s41, s20, 0xffff
	v_readlane_b32 s20, v254, 43
	v_lshl_add_u32 v0, v12, 11, v0
	v_and_b32_e32 v1, 1, v11
	s_add_i32 s57, s18, 0
	v_readlane_b32 s23, v254, 46
	v_lshl_or_b32 v0, v1, 6, v0
	s_or_b32 s54, s51, 0xfffff400
	s_add_i32 s57, s57, 0x26000
	s_mov_b32 s43, s23
	v_mov_b32_e32 v205, v65
	v_lshl_add_u32 v206, v13, 1, v0
	v_mov_b32_e32 v207, v65
	s_mov_b32 s58, 0
	v_add_u32_e32 v243, 0, v16
	s_barrier
	v_readlane_b32 s21, v254, 44
	v_readlane_b32 s22, v254, 45
	s_branch .LBB0_1303

.LBB0_1576:
	s_and_b32 s10, s8, 3
	v_and_b32_e32 v1, 48, v0
	v_lshlrev_b32_e32 v10, 6, v0
	s_movk_i32 s8, 0x3c0
	v_lshlrev_b32_e32 v0, 2, v0
	s_lshl_b32 s34, s5, 6
	s_lshl_b32 s5, s5, 13
	v_and_or_b32 v1, v10, s8, v1
	v_and_b32_e32 v0, 32, v0
	v_lshl_add_u64 v[2:3], s[18:19], 0, v[64:65]
	v_mov_b32_e32 v131, v65
	v_bitop3_b32 v10, v1, s5, v0 bitop3:0xde
	s_lshl_b32 s5, s10, 12
	v_lshl_add_u64 v[4:5], s[18:19], 0, v[130:131]
	v_mov_b32_e32 v135, v65
	v_bitop3_b32 v136, v1, s5, v0 bitop3:0xde
	s_add_i32 m0, s26, 0x18000
	v_lshl_add_u64 v[0:1], v[2:3], 0, s[96:97]
	v_lshl_add_u64 v[6:7], s[16:17], 0, v[134:135]
	v_mov_b32_e32 v133, v65
	global_load_lds_dwordx4 v[0:1], off
	v_lshl_add_u64 v[0:1], v[4:5], 0, s[96:97]
	s_add_i32 m0, s26, 0x1a000
	s_add_i32 s35, s26, 0x8000
	s_add_i32 s36, s26, 0xa000
	v_lshl_add_u64 v[8:9], s[16:17], 0, v[132:133]
	global_load_lds_dwordx4 v[0:1], off
	v_lshl_add_u64 v[0:1], v[6:7], 0, s[96:97]
	s_mov_b32 m0, s35
	s_add_u32 s8, s18, 0x80080
	global_load_lds_dwordx4 v[0:1], off
	v_lshl_add_u64 v[0:1], v[8:9], 0, s[96:97]
	s_mov_b32 m0, s36
	s_addc_u32 s9, s19, 0
	global_load_lds_dwordx4 v[0:1], off
	s_add_i32 m0, s26, 0x1c000
	v_lshl_add_u64 v[0:1], s[8:9], 0, v[64:65]
	global_load_lds_dwordx4 v[0:1], off
	v_lshl_add_u64 v[0:1], s[8:9], 0, v[130:131]
	s_add_i32 m0, s26, 0x1e000
	v_readlane_b32 s12, v254, 43
	global_load_lds_dwordx4 v[0:1], off
	s_waitcnt vmcnt(8)
	s_barrier
	s_waitcnt vmcnt(6)
	s_cmpk_lt_u32 s4, 0x100
	v_readlane_b32 s15, v254, 46
	v_readlane_b32 s4, v253, 23
	s_cselect_b64 s[8:9], -1, 0
	s_lshl_b32 s37, s10, 6
	s_mov_b32 s47, s15
	s_and_b32 s45, s20, 0xffff
	v_add_u32_e32 v137, 0, v10
	v_readlane_b32 s38, v254, 41
	v_readlane_b32 s41, v253, 22
	s_mov_b32 s40, s4
	s_barrier
	v_readlane_b32 s13, v254, 44
	v_readlane_b32 s14, v254, 45
	v_readlane_b32 s5, v253, 24
	s_branch .LBB0_1579

.LBB0_1597:
	s_and_b32 s10, s8, 3
	v_and_b32_e32 v9, 48, v8
	v_lshlrev_b32_e32 v10, 6, v8
	s_movk_i32 s8, 0x3c0
	v_lshlrev_b32_e32 v8, 2, v8
	s_lshl_b32 s34, s5, 6
	s_lshl_b32 s5, s5, 13
	v_and_or_b32 v9, v10, s8, v9
	v_and_b32_e32 v8, 32, v8
	s_add_i32 m0, s26, 0x18000
	v_lshl_add_u64 v[6:7], v[6:7], 0, s[96:97]
	v_bitop3_b32 v10, v9, s5, v8 bitop3:0xde
	s_lshl_b32 s5, s10, 12
	global_load_lds_dwordx4 v[6:7], off
	v_lshl_add_u64 v[4:5], v[4:5], 0, s[96:97]
	s_add_i32 m0, s26, 0x1a000
	s_add_i32 s35, s26, 0x8000
	s_add_i32 s36, s26, 0xa000
	global_load_lds_dwordx4 v[4:5], off
	v_lshl_add_u64 v[0:1], v[0:1], 0, s[96:97]
	s_mov_b32 m0, s35
	s_add_u32 s8, s18, 0x40080
	global_load_lds_dwordx4 v[0:1], off
	v_lshl_add_u64 v[0:1], v[2:3], 0, s[96:97]
	s_mov_b32 m0, s36
	s_addc_u32 s9, s19, 0
	global_load_lds_dwordx4 v[0:1], off
	s_add_i32 m0, s26, 0x1c000
	v_lshl_add_u64 v[0:1], s[8:9], 0, v[64:65]
	global_load_lds_dwordx4 v[0:1], off
	v_lshl_add_u64 v[0:1], s[8:9], 0, v[130:131]
	s_add_i32 m0, s26, 0x1e000
	s_cmpk_lt_u32 s4, 0x100
	global_load_lds_dwordx4 v[0:1], off
	s_waitcnt vmcnt(8)
	s_barrier
	s_waitcnt vmcnt(6)
	v_readlane_b32 s12, v254, 43
	s_cselect_b64 s[8:9], -1, 0
	s_lshl_b32 s4, s10, 6
	v_readlane_b32 s15, v254, 46
	v_bitop3_b32 v136, v9, s5, v8 bitop3:0xde
	s_mov_b32 s47, s15
	s_and_b32 s45, s20, 0xffff
	s_or_b32 s20, s4, 0x1000000
	v_add_u32_e32 v137, 0, v10
	v_readlane_b32 s37, v254, 42
	v_readlane_b32 s40, v253, 33
	v_readlane_b32 s39, v253, 32
	s_barrier
	v_readlane_b32 s13, v254, 44
	v_readlane_b32 s14, v254, 45
	s_branch .LBB0_1600

.LBB0_1618:
	s_add_u32 s10, s0, 0x8ac0000
	s_addc_u32 s11, s1, 0
	s_add_u32 s40, s0, 0xf0c0000
	s_addc_u32 s14, s1, 0
	s_lshl_b32 s7, s7, 5
	v_and_b32_e32 v15, 48, v11
	v_lshlrev_b32_e32 v16, 6, v11
	s_movk_i32 s13, 0x3c0
	v_lshlrev_b32_e32 v11, 2, v11
	s_and_b32 s47, s7, 0x60
	s_add_i32 m0, s37, 0x18000
	v_lshl_add_u64 v[6:7], v[6:7], 0, s[96:97]
	s_lshl_b32 s45, s12, 6
	s_lshl_b32 s12, s12, 13
	v_and_or_b32 v15, v16, s13, v15
	v_and_b32_e32 v11, 32, v11
	s_lshl_b32 s7, s47, 7
	global_load_lds_dwordx4 v[6:7], off
	v_lshl_add_u64 v[4:5], v[4:5], 0, s[96:97]
	s_add_i32 m0, s37, 0x1a000
	s_add_i32 s48, s37, 0x8000
	s_add_i32 s49, s37, 0xa000
	v_bitop3_b32 v16, v15, s12, v11 bitop3:0xde
	global_load_lds_dwordx4 v[4:5], off
	v_lshl_add_u64 v[0:1], v[0:1], 0, s[96:97]
	s_mov_b32 m0, s48
	s_add_u32 s12, s24, 0x80080
	global_load_lds_dwordx4 v[0:1], off
	v_lshl_add_u64 v[0:1], v[2:3], 0, s[96:97]
	s_mov_b32 m0, s49
	s_addc_u32 s13, s25, 0
	global_load_lds_dwordx4 v[0:1], off
	s_add_i32 m0, s37, 0x1c000
	v_lshl_add_u64 v[0:1], s[12:13], 0, v[64:65]
	global_load_lds_dwordx4 v[0:1], off
	v_lshl_add_u64 v[0:1], s[12:13], 0, v[150:151]
	s_add_i32 m0, s37, 0x1e000
	v_readlane_b32 s16, v254, 43
	global_load_lds_dwordx4 v[0:1], off
	s_waitcnt vmcnt(8)
	s_barrier
	v_lshlrev_b32_e32 v0, 15, v13
	v_and_b32_e32 v0, 0xffff0000, v0
	v_lshl_add_u32 v0, v12, 12, v0
	v_and_b32_e32 v1, 1, v13
	v_lshl_or_b32 v0, v1, 6, v0
	v_lshl_add_u32 v156, v14, 1, v0
	v_lshlrev_b32_e32 v0, 15, v8
	v_and_b32_e32 v0, 0xffff0000, v0
	s_waitcnt vmcnt(6)
	v_lshl_add_u32 v0, v9, 12, v0
	v_and_b32_e32 v1, 1, v8
	v_bitop3_b32 v172, s7, v15, v11 bitop3:0xf6
	s_cmpk_lt_u32 s6, 0x100
	v_readlane_b32 s19, v254, 46
	v_lshl_or_b32 v0, v1, 6, v0
	v_readlane_b32 s6, v254, 5
	s_cselect_b64 s[12:13], -1, 0
	s_and_b32 s41, s14, 0xffff
	s_mov_b32 s43, s19
	v_mov_b32_e32 v157, v65
	v_lshl_add_u32 v158, v10, 1, v0
	v_mov_b32_e32 v159, v65
	s_mov_b32 s52, 0
	v_add_u32_e32 v173, 0, v16
	v_readlane_b32 s54, v254, 4
	s_mov_b32 s53, s6
	s_barrier
	v_readlane_b32 s17, v254, 44
	v_readlane_b32 s18, v254, 45
	v_readlane_b32 s7, v254, 6
	s_branch .LBB0_1621

.LBB0_1682:
	s_add_u32 s12, s0, 0x8ac0000
	s_addc_u32 s13, s1, 0
	s_add_u32 s14, s0, 0xf0c0000
	v_and_b32_e32 v9, 48, v8
	v_lshlrev_b32_e32 v10, 6, v8
	s_movk_i32 s16, 0x3c0
	v_lshlrev_b32_e32 v8, 2, v8
	s_addc_u32 s15, s1, 0
	s_lshl_b32 s71, s6, 6
	s_lshl_b32 s6, s6, 13
	v_and_or_b32 v9, v10, s16, v9
	v_and_b32_e32 v8, 32, v8
	v_bitop3_b32 v10, v9, s6, v8 bitop3:0xde
	s_lshl_b32 s6, s7, 5
	s_and_b32 s76, s6, 0x60
	s_add_i32 m0, s63, 0x18000
	v_lshl_add_u64 v[6:7], v[6:7], 0, s[96:97]
	s_lshl_b32 s6, s76, 7
	global_load_lds_dwordx4 v[6:7], off
	v_lshl_add_u64 v[4:5], v[4:5], 0, s[96:97]
	s_add_i32 m0, s63, 0x1a000
	s_add_i32 s77, s63, 0x8000
	s_add_i32 s78, s63, 0xa000
	v_bitop3_b32 v210, s6, v9, v8 bitop3:0xf6
	global_load_lds_dwordx4 v[4:5], off
	v_lshl_add_u64 v[0:1], v[0:1], 0, s[96:97]
	s_mov_b32 m0, s77
	s_add_u32 s6, s44, 0x40080
	global_load_lds_dwordx4 v[0:1], off
	v_lshl_add_u64 v[0:1], v[2:3], 0, s[96:97]
	s_mov_b32 m0, s78
	s_addc_u32 s7, s45, 0
	global_load_lds_dwordx4 v[0:1], off
	s_add_i32 m0, s63, 0x1c000
	v_lshl_add_u64 v[0:1], s[6:7], 0, v[64:65]
	global_load_lds_dwordx4 v[0:1], off
	v_lshl_add_u64 v[0:1], s[6:7], 0, v[190:191]
	s_add_i32 m0, s63, 0x1e000
	s_cmpk_lt_u32 s20, 0x100
	global_load_lds_dwordx4 v[0:1], off
	s_waitcnt vmcnt(8)
	s_barrier
	s_waitcnt vmcnt(6)
	v_readlane_b32 s20, v254, 43
	s_cselect_b64 s[16:17], -1, 0
	s_add_u32 s18, s0, 0x4200
	v_readlane_b32 s23, v254, 46
	s_addc_u32 s19, s1, 0
	s_and_b32 s41, s15, 0xffff
	s_mov_b32 s40, s14
	v_readlane_b32 s22, v254, 45
	s_mov_b32 s43, s23
	s_mov_b32 s79, 0
	v_add_u32_e32 v211, 0, v10
	s_barrier
	v_readlane_b32 s21, v254, 44
	s_branch .LBB0_1685

.LBB0_1744:
	s_add_u32 s71, s8, 0x120000
	v_and_b32_e32 v9, 48, v8
	v_lshlrev_b32_e32 v10, 6, v8
	s_movk_i32 s16, 0x3c0
	v_lshlrev_b32_e32 v8, 2, v8
	s_addc_u32 s76, s9, 0
	s_lshl_b32 s77, s6, 6
	s_lshl_b32 s6, s6, 13
	v_and_or_b32 v9, v10, s16, v9
	v_and_b32_e32 v8, 32, v8
	v_bitop3_b32 v10, v9, s6, v8 bitop3:0xde
	s_lshl_b32 s6, s7, 5
	s_and_b32 s78, s6, 0x60
	s_add_i32 m0, s63, 0x18000
	v_lshl_add_u64 v[6:7], v[6:7], 0, s[96:97]
	s_lshl_b32 s6, s78, 7
	global_load_lds_dwordx4 v[6:7], off
	v_lshl_add_u64 v[4:5], v[4:5], 0, s[96:97]
	s_add_i32 m0, s63, 0x1a000
	s_add_i32 s79, s63, 0x8000
	s_add_i32 s82, s63, 0xa000
	v_bitop3_b32 v154, s6, v9, v8 bitop3:0xf6
	global_load_lds_dwordx4 v[4:5], off
	v_lshl_add_u64 v[0:1], v[0:1], 0, s[96:97]
	s_mov_b32 m0, s79
	s_add_u32 s6, s40, 0x40080
	global_load_lds_dwordx4 v[0:1], off
	v_lshl_add_u64 v[0:1], v[2:3], 0, s[96:97]
	s_mov_b32 m0, s82
	s_addc_u32 s7, s41, 0
	global_load_lds_dwordx4 v[0:1], off
	s_add_i32 m0, s63, 0x1c000
	v_lshl_add_u64 v[0:1], s[6:7], 0, v[64:65]
	global_load_lds_dwordx4 v[0:1], off
	v_lshl_add_u64 v[0:1], s[6:7], 0, v[150:151]
	s_add_i32 m0, s63, 0x1e000
	s_cmpk_lt_u32 s22, 0x100
	global_load_lds_dwordx4 v[0:1], off
	s_waitcnt vmcnt(8)
	s_barrier
	s_waitcnt vmcnt(6)
	v_readlane_b32 s20, v254, 43
	s_cselect_b64 s[16:17], -1, 0
	s_add_u32 s18, s8, 0x4200
	v_readlane_b32 s23, v254, 46
	s_addc_u32 s19, s9, 0
	v_readlane_b32 s22, v254, 45
	s_mov_b32 s51, s23
	s_and_b32 s49, s11, 0xffff
	s_mov_b32 s48, s10
	s_mov_b32 s83, 0
	v_add_u32_e32 v155, 0, v10
	s_barrier
	v_readlane_b32 s21, v254, 44
	s_branch .LBB0_1747

.LBB0_1807:
	s_add_u32 s70, s8, 0x102000
	v_and_b32_e32 v9, 48, v8
	v_lshlrev_b32_e32 v10, 6, v8
	s_movk_i32 s7, 0x3c0
	v_lshlrev_b32_e32 v8, 2, v8
	s_addc_u32 s71, s9, 0
	s_lshl_b32 s76, s1, 6
	s_lshl_b32 s1, s1, 13
	v_and_or_b32 v9, v10, s7, v9
	v_and_b32_e32 v8, 32, v8
	v_bitop3_b32 v10, v9, s1, v8 bitop3:0xde
	s_lshl_b32 s1, s6, 5
	s_and_b32 s77, s1, 0x60
	s_add_i32 m0, s55, 0x18000
	v_lshl_add_u64 v[6:7], v[6:7], 0, s[96:97]
	s_lshl_b32 s1, s77, 7
	global_load_lds_dwordx4 v[6:7], off
	v_lshl_add_u64 v[4:5], v[4:5], 0, s[96:97]
	s_add_i32 m0, s55, 0x1a000
	s_add_i32 s78, s55, 0x8000
	s_add_i32 s79, s55, 0xa000
	global_load_lds_dwordx4 v[4:5], off
	v_lshl_add_u64 v[0:1], v[0:1], 0, s[96:97]
	s_mov_b32 m0, s78
	s_add_u32 s6, s36, 0x40080
	global_load_lds_dwordx4 v[0:1], off
	v_lshl_add_u64 v[0:1], v[2:3], 0, s[96:97]
	s_mov_b32 m0, s79
	s_addc_u32 s7, s37, 0
	global_load_lds_dwordx4 v[0:1], off
	s_add_i32 m0, s55, 0x1c000
	v_lshl_add_u64 v[0:1], s[6:7], 0, v[64:65]
	global_load_lds_dwordx4 v[0:1], off
	v_lshl_add_u64 v[0:1], s[6:7], 0, v[150:151]
	s_add_i32 m0, s55, 0x1e000
	s_cmpk_lt_u32 s20, 0x100
	global_load_lds_dwordx4 v[0:1], off
	s_waitcnt vmcnt(8)
	s_barrier
	s_waitcnt vmcnt(6)
	v_readlane_b32 s20, v254, 43
	s_cselect_b64 s[14:15], -1, 0
	s_add_u32 s16, s8, 0x4200
	v_readlane_b32 s23, v254, 46
	v_bitop3_b32 v154, s1, v9, v8 bitop3:0xf6
	s_addc_u32 s17, s9, 0
	s_mov_b32 s51, s23
	s_and_b32 s49, s49, 0xffff
	s_mov_b32 s82, 0
	v_add_u32_e32 v155, 0, v10
	s_barrier
	v_readlane_b32 s21, v254, 44
	v_readlane_b32 s22, v254, 45
	s_branch .LBB0_1810

.LBB0_1865:
	s_add_u32 s44, s0, 0x112c0000
	s_addc_u32 s14, s1, 0
	s_and_b32 s12, s6, 3
	s_lshl_b32 s48, s7, 6
	v_and_b32_e32 v9, 48, v8
	s_lshl_b32 s6, s7, 13
	v_lshlrev_b32_e32 v10, 6, v8
	s_movk_i32 s7, 0x3c0
	v_lshlrev_b32_e32 v8, 2, v8
	v_and_or_b32 v9, v10, s7, v9
	v_and_b32_e32 v8, 32, v8
	s_add_i32 m0, s39, 0x18000
	v_lshl_add_u64 v[6:7], v[6:7], 0, s[96:97]
	v_bitop3_b32 v10, v9, s6, v8 bitop3:0xde
	s_lshl_b32 s6, s12, 12
	global_load_lds_dwordx4 v[6:7], off
	v_lshl_add_u64 v[4:5], v[4:5], 0, s[96:97]
	s_add_i32 m0, s39, 0x1a000
	s_add_i32 s49, s39, 0x8000
	s_add_i32 s51, s39, 0xa000
	v_bitop3_b32 v136, v9, s6, v8 bitop3:0xde
	global_load_lds_dwordx4 v[4:5], off
	v_lshl_add_u64 v[0:1], v[0:1], 0, s[96:97]
	s_mov_b32 m0, s49
	s_add_u32 s6, s22, 0x40080
	global_load_lds_dwordx4 v[0:1], off
	v_lshl_add_u64 v[0:1], v[2:3], 0, s[96:97]
	s_mov_b32 m0, s51
	s_addc_u32 s7, s23, 0
	global_load_lds_dwordx4 v[0:1], off
	s_add_i32 m0, s39, 0x1c000
	v_lshl_add_u64 v[0:1], s[6:7], 0, v[64:65]
	global_load_lds_dwordx4 v[0:1], off
	v_lshl_add_u64 v[0:1], s[6:7], 0, v[134:135]
	s_add_i32 m0, s39, 0x1e000
	s_cmpk_lt_u32 s16, 0x100
	global_load_lds_dwordx4 v[0:1], off
	s_waitcnt vmcnt(8)
	s_barrier
	s_waitcnt vmcnt(6)
	s_cselect_b64 s[10:11], -1, 0
	s_lshl_b32 s52, s12, 6
	v_readlane_b32 s16, v254, 43
	s_add_u32 s12, s0, 0x4200
	v_readlane_b32 s19, v254, 46
	v_readlane_b32 s6, v254, 18
	s_addc_u32 s13, s1, 0
	s_and_b32 s45, s14, 0xffff
	s_mov_b32 s47, s19
	s_mov_b32 s53, 0
	v_add_u32_e32 v137, 0, v10
	v_readlane_b32 s57, v253, 46
	s_mov_b32 s55, s6
	s_barrier
	v_readlane_b32 s17, v254, 44
	v_readlane_b32 s18, v254, 45
	v_readlane_b32 s7, v254, 19
	s_branch .LBB0_1868

.LBB0_2419:
	s_add_u32 s8, s6, 0x8ac0000
	s_addc_u32 s9, s7, 0
	v_and_b32_e32 v15, 48, v14
	v_lshlrev_b32_e32 v16, 6, v14
	s_movk_i32 s7, 0x3c0
	v_lshlrev_b32_e32 v14, 2, v14
	s_lshl_b32 s6, s12, 13
	v_and_or_b32 v15, v16, s7, v15
	v_and_b32_e32 v14, 32, v14
	v_bitop3_b32 v16, v15, s6, v14 bitop3:0xde
	s_lshl_b32 s6, s11, 5
	s_and_b32 s47, s6, 0x60
	s_add_i32 m0, s41, 0x18000
	v_lshl_add_u64 v[6:7], v[6:7], 0, s[96:97]
	s_lshl_b32 s45, s12, 6
	s_lshl_b32 s6, s47, 7
	global_load_lds_dwordx4 v[6:7], off
	v_lshl_add_u64 v[4:5], v[4:5], 0, s[96:97]
	s_add_i32 m0, s41, 0x1a000
	s_add_i32 s48, s41, 0x8000
	s_add_i32 s49, s41, 0xa000
	v_bitop3_b32 v144, s6, v15, v14 bitop3:0xf6
	global_load_lds_dwordx4 v[4:5], off
	v_lshl_add_u64 v[0:1], v[0:1], 0, s[96:97]
	s_mov_b32 m0, s48
	s_add_u32 s6, s28, 0x40080
	global_load_lds_dwordx4 v[0:1], off
	v_lshl_add_u64 v[0:1], v[2:3], 0, s[96:97]
	s_mov_b32 m0, s49
	s_addc_u32 s7, s29, 0
	global_load_lds_dwordx4 v[0:1], off
	s_add_i32 m0, s41, 0x1c000
	v_lshl_add_u64 v[0:1], s[6:7], 0, v[64:65]
	global_load_lds_dwordx4 v[0:1], off
	v_lshl_add_u64 v[0:1], s[6:7], 0, v[130:131]
	s_add_i32 m0, s41, 0x1e000
	s_cmpk_lt_u32 s10, 0x100
	global_load_lds_dwordx4 v[0:1], off
	s_waitcnt vmcnt(8)
	s_barrier
	v_lshlrev_b32_e32 v0, 14, v12
	v_and_b32_e32 v0, 0xffff8000, v0
	v_lshl_add_u32 v0, v11, 11, v0
	v_and_b32_e32 v1, 1, v12
	v_lshl_or_b32 v0, v1, 6, v0
	v_lshl_add_u32 v136, v13, 1, v0
	v_lshlrev_b32_e32 v0, 14, v8
	v_and_b32_e32 v0, 0xffff8000, v0
	s_waitcnt vmcnt(6)
	v_lshl_add_u32 v0, v9, 11, v0
	v_and_b32_e32 v1, 1, v8
	v_lshl_or_b32 v0, v1, 6, v0
	s_cselect_b64 s[10:11], -1, 0
	v_mov_b32_e32 v137, v65
	v_lshl_add_u32 v138, v10, 1, v0
	v_mov_b32_e32 v139, v65
	s_mov_b32 s51, 0
	v_add_u32_e32 v145, 0, v16
	s_barrier
	s_branch .LBB0_2422

.LBB0_2487:
	v_readlane_b32 s12, v255, 2
	v_readlane_b32 s13, v255, 3
	s_lshl_b64 s[12:13], s[12:13], 2
	s_add_u32 s7, s10, s12
	s_addc_u32 s10, s11, s13
	s_add_u32 s34, s7, 0x105000
	s_addc_u32 s35, s10, 0
	s_lshl_b32 s5, s5, 5
	v_and_b32_e32 v17, 48, v16
	v_lshlrev_b32_e32 v18, 6, v16
	s_movk_i32 s7, 0x3c0
	v_lshlrev_b32_e32 v16, 2, v16
	s_and_b32 s37, s5, 0x60
	s_add_i32 m0, s27, 0x18000
	v_lshl_add_u64 v[6:7], v[6:7], 0, s[96:97]
	s_lshl_b32 s36, s6, 6
	s_lshl_b32 s6, s6, 13
	v_and_or_b32 v17, v18, s7, v17
	v_and_b32_e32 v16, 32, v16
	s_lshl_b32 s5, s37, 7
	global_load_lds_dwordx4 v[6:7], off
	v_lshl_add_u64 v[4:5], v[4:5], 0, s[96:97]
	s_add_i32 m0, s27, 0x1a000
	s_add_i32 s38, s27, 0x8000
	s_add_i32 s39, s27, 0xa000
	v_bitop3_b32 v18, v17, s6, v16 bitop3:0xde
	global_load_lds_dwordx4 v[4:5], off
	v_lshl_add_u64 v[0:1], v[0:1], 0, s[96:97]
	s_mov_b32 m0, s38
	s_add_u32 s6, s16, 0xb0080
	global_load_lds_dwordx4 v[0:1], off
	v_lshl_add_u64 v[0:1], v[2:3], 0, s[96:97]
	s_mov_b32 m0, s39
	s_addc_u32 s7, s17, 0
	global_load_lds_dwordx4 v[0:1], off
	s_add_i32 m0, s27, 0x1c000
	v_lshl_add_u64 v[0:1], s[6:7], 0, v[64:65]
	global_load_lds_dwordx4 v[0:1], off
	v_lshl_add_u64 v[0:1], s[6:7], 0, v[146:147]
	s_add_i32 m0, s27, 0x1e000
	v_bitop3_b32 v158, s5, v17, v16 bitop3:0xf6
	global_load_lds_dwordx4 v[0:1], off
	s_waitcnt vmcnt(8)
	s_barrier
	s_cmpk_lt_u32 s4, 0x100
	v_readlane_b32 s4, v254, 43
	v_readlane_b32 s6, v254, 45
	v_readlane_b32 s7, v254, 46
	s_movk_i32 s6, 0xb00
	v_readlane_b32 s5, v254, 44
	s_mov_b32 s51, s7
	v_lshrrev_b32_e32 v1, 1, v13
	v_mul_lo_u32 v0, v12, s6
	s_mov_b32 s7, 0xb000
	v_mad_u64_u32 v[0:1], s[4:5], v1, s7, v[0:1]
	v_or_b32_e32 v0, v0, v14
	v_add_lshl_u32 v0, v0, v15, 1
	v_mov_b32_e32 v1, v65
	s_mov_b64 s[12:13], 0xb0080
	v_lshl_add_u64 v[152:153], v[0:1], 0, s[12:13]
	v_lshrrev_b32_e32 v1, 1, v8
	v_mul_lo_u32 v0, v9, s6
	v_mad_u64_u32 v[0:1], s[4:5], v1, s7, v[0:1]
	s_waitcnt vmcnt(6)
	v_or_b32_e32 v0, v0, v10
	v_add_lshl_u32 v0, v0, v11, 1
	v_mov_b32_e32 v1, v65
	v_readlane_b32 s4, v254, 5
	s_cselect_b64 s[10:11], -1, 0
	s_and_b32 s49, s9, 0xffff
	s_mov_b32 s48, s8
	v_lshl_add_u64 v[154:155], v[0:1], 0, s[12:13]
	s_mov_b32 s40, 0
	v_add_u32_e32 v159, 0, v18
	v_readlane_b32 s45, v254, 4
	s_mov_b32 s44, s4
	s_barrier
	v_readlane_b32 s5, v254, 6
	s_branch .LBB0_2490

.LBB0_2512:
	s_add_u32 s44, s2, 0x46c0000
	s_addc_u32 s7, s3, 0
	v_and_b32_e32 v9, 48, v8
	v_lshlrev_b32_e32 v10, 6, v8
	s_movk_i32 s3, 0x3c0
	v_lshlrev_b32_e32 v8, 2, v8
	s_lshl_b32 s2, s6, 13
	v_and_or_b32 v9, v10, s3, v9
	v_and_b32_e32 v8, 32, v8
	v_bitop3_b32 v10, v9, s2, v8 bitop3:0xde
	s_lshl_b32 s2, s5, 5
	s_and_b32 s24, s2, 0x60
	s_add_i32 m0, s19, 0x18000
	v_lshl_add_u64 v[6:7], v[6:7], 0, s[96:97]
	s_lshl_b32 s23, s6, 6
	s_lshl_b32 s2, s24, 7
	global_load_lds_dwordx4 v[6:7], off
	v_lshl_add_u64 v[4:5], v[4:5], 0, s[96:97]
	s_add_i32 m0, s19, 0x1a000
	s_add_i32 s25, s19, 0x8000
	s_add_i32 s26, s19, 0xa000
	v_bitop3_b32 v136, s2, v9, v8 bitop3:0xf6
	global_load_lds_dwordx4 v[4:5], off
	v_lshl_add_u64 v[0:1], v[0:1], 0, s[96:97]
	s_mov_b32 m0, s25
	s_add_u32 s2, s12, 0xb0080
	global_load_lds_dwordx4 v[0:1], off
	v_lshl_add_u64 v[0:1], v[2:3], 0, s[96:97]
	s_mov_b32 m0, s26
	s_addc_u32 s3, s13, 0
	global_load_lds_dwordx4 v[0:1], off
	s_add_i32 m0, s19, 0x1c000
	v_lshl_add_u64 v[0:1], s[2:3], 0, v[64:65]
	global_load_lds_dwordx4 v[0:1], off
	v_lshl_add_u64 v[0:1], s[2:3], 0, v[130:131]
	s_add_i32 m0, s19, 0x1e000
	v_readlane_b32 s36, v254, 43
	global_load_lds_dwordx4 v[0:1], off
	s_waitcnt vmcnt(8)
	s_barrier
	s_waitcnt vmcnt(6)
	s_cmpk_lt_u32 s4, 0x100
	v_readlane_b32 s39, v254, 46
	s_cselect_b64 s[4:5], -1, 0
	s_and_b32 s45, s7, 0xffff
	s_mov_b32 s47, s39
	v_add_u32_e32 v137, 0, v10
	v_readlane_b32 s27, v254, 49
	v_readlane_b32 s31, v253, 52
	v_readlane_b32 s34, v253, 51
	s_barrier
	v_readlane_b32 s37, v254, 44
	v_readlane_b32 s38, v254, 45
	s_branch .LBB0_2515
